# short gated conv branch: both items of an unrolled pair load together (second item's loads hoisted above the first item's compute, counted waits)
# speedup vs baseline: 1.0007x; 1.0007x over previous
; __device__ __forceinline__ unsigned cvt_pk_bf16(float lo, float hi) { unsigned r; asm volatile("v_cvt_pk_bf16_f32 %0, %1, %2" : "=v"(r) : "v"(lo), "v"(hi)); return r; }
; __device__ __forceinline__ float bflo(unsigned w) { return __uint_as_float(w << 16); }
; __device__ __forceinline__ float bfhi(unsigned w) { return __uint_as_float(w & 0xffff0000u); }
; __device__ __forceinline__ void conv_unit(LAS unsigned char* lds, const bf16_t* PROJ, bf16_t* YCAT, const float* wshort, const float* dwb, const float* lng, const float* lnb, int bg, int bl, int tb, int tid, int wave, int lane) {
;     ...
; #pragma unroll 2
;         for (int it = 0; it < 4; ++it) {
;             const int tok = (tid >> 5) + 16 * it, t = t0 + tok;
;             const bf16_t* src = PROJ + (prow + t) * NPROJ + 768 + 8 * grp;
;             u32x4 c[3], x[3];
; #pragma unroll
;             for (int k = 0; k < 3; ++k) {
;                 const int tt = t - 2 + k, dk = (tt >= 0) ? (k - 2) : 0;
;                 c[k] = *(const u32x4*)(src + dk * NPROJ + 256); x[k] = *(const u32x4*)(src + dk * NPROJ + 512);
;             }
;             const u32x4 b = *(const u32x4*)src;
; #pragma unroll
;             for (int k = 0; k < 3; ++k) if (t - 2 + k < 0) c[k] = (u32x4){0u, 0u, 0u, 0u};
;             float acc[8];
; #pragma unroll
;             for (int e = 0; e < 8; ++e) acc[e] = 0.f;
; #pragma unroll
;             for (int k = 0; k < 3; ++k) {
;                 acc[0] += w0[k][0] * (bflo(c[k].x) * bflo(x[k].x)); acc[1] += w0[k][1] * (bfhi(c[k].x) * bfhi(x[k].x)); acc[2] += w0[k][2] * (bflo(c[k].y) * bflo(x[k].y)); acc[3] += w0[k][3] * (bfhi(c[k].y) * bfhi(x[k].y));
;                 acc[4] += w1[k][0] * (bflo(c[k].z) * bflo(x[k].z)); acc[5] += w1[k][1] * (bfhi(c[k].z) * bfhi(x[k].z)); acc[6] += w1[k][2] * (bflo(c[k].w) * bflo(x[k].w)); acc[7] += w1[k][3] * (bfhi(c[k].w) * bfhi(x[k].w));
;             }
;             u32x4 w; w.x = cvt_pk_bf16(bflo(b.x) * acc[0], bfhi(b.x) * acc[1]); w.y = cvt_pk_bf16(bflo(b.y) * acc[2], bfhi(b.y) * acc[3]); w.z = cvt_pk_bf16(bflo(b.z) * acc[4], bfhi(b.z) * acc[5]); w.w = cvt_pk_bf16(bflo(b.w) * acc[6], bfhi(b.w) * acc[7]);
;             *(u32x4*)(YCAT + (grow + t) * YW + 256 + 8 * grp) = w;
.LBB0_390:
	v_add_u32_e32 v0, s66, v44
	v_cmp_gt_i32_e32 vcc, 2, v0
	v_lshl_add_u64 v[84:85], v[32:33], 0, v[64:65]
	v_cmp_gt_i32_e64 s[20:21], 1, v0
	v_cndmask_b32_e64 v19, -1, 0, vcc
	v_cndmask_b32_e64 v18, v239, 0, vcc
	v_lshl_add_u64 v[38:39], v[84:85], 0, v[18:19]
	global_load_dwordx4 v[18:21], v[38:39], off
	s_nop 0
	global_load_dwordx4 v[38:41], v[38:39], off offset:512
	v_cndmask_b32_e64 v69, -1, 0, s[20:21]
	v_cndmask_b32_e64 v68, v240, 0, s[20:21]
	v_lshl_add_u64 v[72:73], v[84:85], 0, v[68:69]
	global_load_dwordx4 v[68:71], v[72:73], off
	s_nop 0
	global_load_dwordx4 v[72:75], v[72:73], off offset:512
	s_nop 0
	global_load_dwordx4 v[76:79], v[84:85], off
	global_load_dwordx4 v[80:83], v[84:85], off offset:512
	s_nop 0
	global_load_dwordx4 v[84:87], v[84:85], off offset:-512
	s_add_i32 s67, s67, -2
	s_add_i32 s66, s66, 32
	v_lshl_add_u64 v[32:33], v[32:33], 0, s[64:65]
	s_cmp_eq_u32 s67, 0
	v_add_u32_e32 v186, 16, v0
	v_lshl_add_u64 v[178:179], v[34:35], 0, v[64:65]
	v_mov_b32_e32 v153, -1
	v_mov_b32_e32 v152, v239
	v_lshl_add_u64 v[156:157], v[178:179], 0, v[152:153]
	global_load_dwordx4 v[152:155], v[156:157], off
	s_nop 0
	global_load_dwordx4 v[156:159], v[156:157], off offset:512
	v_mov_b32_e32 v163, -1
	v_mov_b32_e32 v162, v240
	v_lshl_add_u64 v[166:167], v[178:179], 0, v[162:163]
	global_load_dwordx4 v[162:165], v[166:167], off
	s_nop 0
	global_load_dwordx4 v[166:169], v[166:167], off offset:512
	s_nop 0
	global_load_dwordx4 v[170:173], v[178:179], off
	global_load_dwordx4 v[174:177], v[178:179], off offset:512
	s_nop 0
	global_load_dwordx4 v[178:181], v[178:179], off offset:-512
	s_waitcnt vmcnt(13)
	v_cndmask_b32_e64 v21, v21, 0, vcc
	v_cndmask_b32_e64 v20, v20, 0, vcc
	v_cndmask_b32_e64 v19, v19, 0, vcc
	v_cndmask_b32_e64 v18, v18, 0, vcc
	v_cmp_lt_i32_e32 vcc, -1, v0
	s_waitcnt vmcnt(11)
	v_cndmask_b32_e64 v67, v71, 0, s[20:21]
	v_lshlrev_b32_e32 v88, 16, v18
	s_waitcnt vmcnt(9)
	v_cndmask_b32_e32 v71, 0, v79, vcc
	v_lshlrev_b32_e32 v79, 16, v38
	v_and_b32_e32 v18, 0xffff0000, v18
	v_and_b32_e32 v38, 0xffff0000, v38
	v_mul_f32_e32 v18, v18, v38
	v_mul_f32_e32 v79, v88, v79
	v_fma_f32 v38, v3, v18, 0
	v_lshlrev_b32_e32 v18, 16, v39
	v_lshlrev_b32_e32 v88, 16, v19
	v_mul_f32_e32 v18, v88, v18
	v_fma_f32 v88, v4, v18, 0
	v_and_b32_e32 v18, 0xffff0000, v19
	v_and_b32_e32 v19, 0xffff0000, v39
	v_mul_f32_e32 v18, v18, v19
	v_fma_f32 v39, v5, v18, 0
	v_lshlrev_b32_e32 v18, 16, v40
	v_lshlrev_b32_e32 v19, 16, v20
	v_mul_f32_e32 v18, v19, v18
	v_fma_f32 v89, v6, v18, 0
	v_and_b32_e32 v18, 0xffff0000, v20
	v_and_b32_e32 v19, 0xffff0000, v40
	v_mul_f32_e32 v18, v18, v19
	v_fma_f32 v40, v7, v18, 0
	v_lshlrev_b32_e32 v18, 16, v41
	v_lshlrev_b32_e32 v19, 16, v21
	v_mul_f32_e32 v18, v19, v18
	v_fma_f32 v90, v8, v18, 0
	v_and_b32_e32 v18, 0xffff0000, v21
	v_and_b32_e32 v19, 0xffff0000, v41
	v_cndmask_b32_e64 v68, v68, 0, s[20:21]
	v_cndmask_b32_e32 v76, 0, v76, vcc
	v_mul_f32_e32 v18, v18, v19
	v_fma_f32 v41, v9, v18, 0
	v_lshlrev_b32_e32 v18, 16, v76
	v_lshlrev_b32_e32 v19, 16, v68
	v_lshlrev_b32_e32 v21, 16, v72
	s_waitcnt vmcnt(8)
	v_lshlrev_b32_e32 v20, 16, v80
	v_pk_mul_f32 v[18:19], v[20:21], v[18:19]
	v_fma_f32 v79, v2, v79, 0
	v_pk_mul_f32 v[18:19], v[28:29], v[18:19]
	v_and_b32_e32 v21, 0xffff0000, v72
	v_add_f32_e32 v19, v79, v19
	v_add_f32_e32 v79, v18, v19
	v_and_b32_e32 v19, 0xffff0000, v68
	v_and_b32_e32 v18, 0xffff0000, v76
	v_and_b32_e32 v20, 0xffff0000, v80
	v_pk_mul_f32 v[18:19], v[20:21], v[18:19]
	v_cndmask_b32_e64 v69, v69, 0, s[20:21]
	v_pk_mul_f32 v[18:19], v[10:11], v[18:19]
	v_cndmask_b32_e32 v77, 0, v77, vcc
	v_add_f32_e32 v19, v38, v19
	v_add_f32_e32 v38, v18, v19
	v_lshlrev_b32_e32 v18, 16, v77
	v_lshlrev_b32_e32 v19, 16, v69
	v_lshlrev_b32_e32 v21, 16, v73
	v_lshlrev_b32_e32 v20, 16, v81
	v_pk_mul_f32 v[18:19], v[20:21], v[18:19]
	v_and_b32_e32 v21, 0xffff0000, v73
	v_pk_mul_f32 v[18:19], v[26:27], v[18:19]
	v_and_b32_e32 v20, 0xffff0000, v81
	v_add_f32_e32 v19, v88, v19
	v_add_f32_e32 v68, v18, v19
	v_and_b32_e32 v19, 0xffff0000, v69
	v_and_b32_e32 v18, 0xffff0000, v77
	v_pk_mul_f32 v[18:19], v[20:21], v[18:19]
	v_cndmask_b32_e64 v70, v70, 0, s[20:21]
	v_pk_mul_f32 v[18:19], v[12:13], v[18:19]
	v_cndmask_b32_e32 v78, 0, v78, vcc
	v_add_f32_e32 v19, v39, v19
	v_add_f32_e32 v39, v18, v19
	v_lshlrev_b32_e32 v18, 16, v78
	v_lshlrev_b32_e32 v19, 16, v70
	v_lshlrev_b32_e32 v21, 16, v74
	v_lshlrev_b32_e32 v20, 16, v82
	v_pk_mul_f32 v[18:19], v[20:21], v[18:19]
	v_and_b32_e32 v21, 0xffff0000, v74
	v_pk_mul_f32 v[18:19], v[24:25], v[18:19]
	v_and_b32_e32 v20, 0xffff0000, v82
	v_add_f32_e32 v19, v89, v19
	v_add_f32_e32 v69, v18, v19
	v_and_b32_e32 v19, 0xffff0000, v70
	v_and_b32_e32 v18, 0xffff0000, v78
	v_pk_mul_f32 v[18:19], v[20:21], v[18:19]
	v_lshlrev_b32_e32 v21, 16, v75
	v_pk_mul_f32 v[18:19], v[14:15], v[18:19]
	v_lshlrev_b32_e32 v20, 16, v83
	v_add_f32_e32 v19, v40, v19
	v_add_f32_e32 v40, v18, v19
	v_lshlrev_b32_e32 v18, 16, v71
	v_lshlrev_b32_e32 v19, 16, v67
	v_pk_mul_f32 v[18:19], v[20:21], v[18:19]
	v_and_b32_e32 v21, 0xffff0000, v75
	v_pk_mul_f32 v[18:19], v[22:23], v[18:19]
	v_and_b32_e32 v20, 0xffff0000, v83
	v_add_f32_e32 v19, v90, v19
	v_add_f32_e32 v70, v18, v19
	v_and_b32_e32 v19, 0xffff0000, v67
	v_and_b32_e32 v18, 0xffff0000, v71
	v_pk_mul_f32 v[18:19], v[20:21], v[18:19]
	s_waitcnt vmcnt(7)
; __device__ __forceinline__ unsigned cvt_pk_bf16(float lo, float hi) { unsigned r; asm volatile("v_cvt_pk_bf16_f32 %0, %1, %2" : "=v"(r) : "v"(lo), "v"(hi)); return r; }
; __device__ __forceinline__ float bflo(unsigned w) { return __uint_as_float(w << 16); }
; __device__ __forceinline__ float bfhi(unsigned w) { return __uint_as_float(w & 0xffff0000u); }
; __device__ __forceinline__ void conv_unit(LAS unsigned char* lds, const bf16_t* PROJ, bf16_t* YCAT, const float* wshort, const float* dwb, const float* lng, const float* lnb, int bg, int bl, int tb, int tid, int wave, int lane) {
;     ...
; #pragma unroll 2
;         for (int it = 0; it < 4; ++it) {
;             const int tok = (tid >> 5) + 16 * it, t = t0 + tok;
;             const bf16_t* src = PROJ + (prow + t) * NPROJ + 768 + 8 * grp;
;             u32x4 c[3], x[3];
; #pragma unroll
;             for (int k = 0; k < 3; ++k) {
;                 const int tt = t - 2 + k, dk = (tt >= 0) ? (k - 2) : 0;
;                 c[k] = *(const u32x4*)(src + dk * NPROJ + 256); x[k] = *(const u32x4*)(src + dk * NPROJ + 512);
;             }
;             const u32x4 b = *(const u32x4*)src;
; #pragma unroll
;             for (int k = 0; k < 3; ++k) if (t - 2 + k < 0) c[k] = (u32x4){0u, 0u, 0u, 0u};
;             float acc[8];
; #pragma unroll
;             for (int e = 0; e < 8; ++e) acc[e] = 0.f;
; #pragma unroll
;             for (int k = 0; k < 3; ++k) {
;                 acc[0] += w0[k][0] * (bflo(c[k].x) * bflo(x[k].x)); acc[1] += w0[k][1] * (bfhi(c[k].x) * bfhi(x[k].x)); acc[2] += w0[k][2] * (bflo(c[k].y) * bflo(x[k].y)); acc[3] += w0[k][3] * (bfhi(c[k].y) * bfhi(x[k].y));
;                 acc[4] += w1[k][0] * (bflo(c[k].z) * bflo(x[k].z)); acc[5] += w1[k][1] * (bfhi(c[k].z) * bfhi(x[k].z)); acc[6] += w1[k][2] * (bflo(c[k].w) * bflo(x[k].w)); acc[7] += w1[k][3] * (bfhi(c[k].w) * bfhi(x[k].w));
;             }
;             u32x4 w; w.x = cvt_pk_bf16(bflo(b.x) * acc[0], bfhi(b.x) * acc[1]); w.y = cvt_pk_bf16(bflo(b.y) * acc[2], bfhi(b.y) * acc[3]); w.z = cvt_pk_bf16(bflo(b.z) * acc[4], bfhi(b.z) * acc[5]); w.w = cvt_pk_bf16(bflo(b.w) * acc[6], bfhi(b.w) * acc[7]);
;             *(u32x4*)(YCAT + (grow + t) * YW + 256 + 8 * grp) = w;
	v_and_b32_e32 v20, 0xffff0000, v85
	v_pk_mul_f32 v[18:19], v[16:17], v[18:19]
	v_mul_f32_e32 v20, v39, v20
	v_add_f32_e32 v19, v41, v19
	v_add_f32_e32 v21, v18, v19
	v_lshlrev_b32_e32 v18, 16, v84
	v_and_b32_e32 v19, 0xffff0000, v84
	v_mul_f32_e32 v18, v79, v18
	v_mul_f32_e32 v19, v38, v19
	v_cvt_pk_bf16_f32 v18, v18, v19
	v_lshlrev_b32_e32 v19, 16, v85
	v_mul_f32_e32 v19, v68, v19
	v_cvt_pk_bf16_f32 v19, v19, v20
	v_lshlrev_b32_e32 v20, 16, v86
	v_and_b32_e32 v38, 0xffff0000, v86
	v_mul_f32_e32 v20, v69, v20
	v_mul_f32_e32 v38, v40, v38
	v_cvt_pk_bf16_f32 v20, v20, v38
	v_lshlrev_b32_e32 v38, 16, v87
	v_and_b32_e32 v39, 0xffff0000, v87
	v_mul_f32_e32 v38, v70, v38
	v_mul_f32_e32 v21, v21, v39
	v_add_u32_e32 v0, 16, v0
	v_cvt_pk_bf16_f32 v21, v38, v21
	v_lshl_add_u64 v[38:39], v[36:37], 0, v[64:65]
	v_cmp_gt_i32_e32 vcc, 2, v0
	global_store_dwordx4 v[38:39], v[18:21], off
	v_lshl_add_u64 v[34:35], v[34:35], 0, s[64:65]
	v_lshl_add_u64 v[36:37], v[36:37], 0, s[62:63]
	v_cmp_gt_i32_e32 vcc, 2, v186
	v_cmp_gt_i32_e64 s[20:21], 1, v186
	s_waitcnt vmcnt(7)
	v_cndmask_b32_e64 v155, v155, 0, vcc
	v_cndmask_b32_e64 v154, v154, 0, vcc
	v_cndmask_b32_e64 v153, v153, 0, vcc
	v_cndmask_b32_e64 v152, v152, 0, vcc
	v_cmp_lt_i32_e32 vcc, -1, v186
	s_waitcnt vmcnt(5)
	v_cndmask_b32_e64 v161, v165, 0, s[20:21]
	v_cndmask_b32_e64 v162, v162, 0, s[20:21]
	s_waitcnt vmcnt(3)
	v_cndmask_b32_e32 v186, 0, v173, vcc
	v_cndmask_b32_e32 v165, 0, v172, vcc
	v_lshlrev_b32_e32 v172, 16, v156
	v_lshlrev_b32_e32 v173, 16, v152
	v_and_b32_e32 v152, 0xffff0000, v152
	v_and_b32_e32 v156, 0xffff0000, v156
	v_mul_f32_e32 v152, v152, v156
	v_mul_f32_e32 v172, v173, v172
	v_fma_f32 v156, v3, v152, 0
	v_lshlrev_b32_e32 v152, 16, v157
	v_lshlrev_b32_e32 v173, 16, v153
	v_mul_f32_e32 v152, v173, v152
	v_fma_f32 v173, v4, v152, 0
	v_and_b32_e32 v152, 0xffff0000, v153
	v_and_b32_e32 v153, 0xffff0000, v157
	v_mul_f32_e32 v152, v152, v153
	v_fma_f32 v157, v5, v152, 0
	v_lshlrev_b32_e32 v152, 16, v158
	v_lshlrev_b32_e32 v153, 16, v154
	v_mul_f32_e32 v152, v153, v152
	v_fma_f32 v182, v6, v152, 0
	v_and_b32_e32 v152, 0xffff0000, v154
	v_and_b32_e32 v153, 0xffff0000, v158
	v_mul_f32_e32 v152, v152, v153
	v_fma_f32 v158, v7, v152, 0
	v_lshlrev_b32_e32 v152, 16, v159
	v_lshlrev_b32_e32 v153, 16, v155
	v_mul_f32_e32 v152, v153, v152
	v_fma_f32 v183, v8, v152, 0
	v_and_b32_e32 v152, 0xffff0000, v155
	v_and_b32_e32 v153, 0xffff0000, v159
	v_cndmask_b32_e32 v170, 0, v170, vcc
	v_mul_f32_e32 v152, v152, v153
	v_fma_f32 v159, v9, v152, 0
	v_lshlrev_b32_e32 v153, 16, v162
	v_lshlrev_b32_e32 v152, 16, v170
	v_lshlrev_b32_e32 v155, 16, v166
	s_waitcnt vmcnt(2)
	v_lshlrev_b32_e32 v154, 16, v174
	v_pk_mul_f32 v[152:153], v[154:155], v[152:153]
	v_fma_f32 v172, v2, v172, 0
	v_pk_mul_f32 v[152:153], v[28:29], v[152:153]
	v_and_b32_e32 v155, 0xffff0000, v166
	v_add_f32_e32 v153, v172, v153
	v_add_f32_e32 v172, v152, v153
	v_and_b32_e32 v153, 0xffff0000, v162
	v_and_b32_e32 v152, 0xffff0000, v170
	v_and_b32_e32 v154, 0xffff0000, v174
	v_pk_mul_f32 v[152:153], v[154:155], v[152:153]
	v_cndmask_b32_e64 v163, v163, 0, s[20:21]
	v_pk_mul_f32 v[152:153], v[10:11], v[152:153]
	v_cndmask_b32_e32 v171, 0, v171, vcc
	v_add_f32_e32 v153, v156, v153
	v_add_f32_e32 v156, v152, v153
	v_lshlrev_b32_e32 v153, 16, v163
	v_lshlrev_b32_e32 v152, 16, v171
	v_lshlrev_b32_e32 v155, 16, v167
	v_lshlrev_b32_e32 v154, 16, v175
	v_pk_mul_f32 v[152:153], v[154:155], v[152:153]
	v_and_b32_e32 v155, 0xffff0000, v167
	v_pk_mul_f32 v[152:153], v[26:27], v[152:153]
	v_and_b32_e32 v154, 0xffff0000, v175
	v_add_f32_e32 v153, v173, v153
	v_add_f32_e32 v162, v152, v153
	v_and_b32_e32 v153, 0xffff0000, v163
	v_and_b32_e32 v152, 0xffff0000, v171
	v_pk_mul_f32 v[152:153], v[154:155], v[152:153]
	v_cndmask_b32_e64 v164, v164, 0, s[20:21]
	v_pk_mul_f32 v[152:153], v[12:13], v[152:153]
	v_lshlrev_b32_e32 v155, 16, v168
	v_add_f32_e32 v153, v157, v153
	v_add_f32_e32 v157, v152, v153
	v_lshlrev_b32_e32 v153, 16, v164
	v_lshlrev_b32_e32 v152, 16, v165
	v_lshlrev_b32_e32 v154, 16, v176
	v_pk_mul_f32 v[152:153], v[154:155], v[152:153]
	v_and_b32_e32 v155, 0xffff0000, v168
	v_pk_mul_f32 v[152:153], v[24:25], v[152:153]
	v_and_b32_e32 v154, 0xffff0000, v176
	v_add_f32_e32 v153, v182, v153
	v_add_f32_e32 v163, v152, v153
	v_and_b32_e32 v153, 0xffff0000, v164
	v_and_b32_e32 v152, 0xffff0000, v165
	v_pk_mul_f32 v[152:153], v[154:155], v[152:153]
	v_lshlrev_b32_e32 v155, 16, v169
	v_pk_mul_f32 v[152:153], v[14:15], v[152:153]
	v_lshlrev_b32_e32 v154, 16, v177
	v_add_f32_e32 v153, v158, v153
	v_add_f32_e32 v158, v152, v153
	v_lshlrev_b32_e32 v153, 16, v161
	v_lshlrev_b32_e32 v152, 16, v186
	v_pk_mul_f32 v[152:153], v[154:155], v[152:153]
	v_and_b32_e32 v155, 0xffff0000, v169
	v_pk_mul_f32 v[152:153], v[22:23], v[152:153]
	v_and_b32_e32 v154, 0xffff0000, v177
	v_add_f32_e32 v153, v183, v153
	v_add_f32_e32 v164, v152, v153
	v_and_b32_e32 v153, 0xffff0000, v161
	v_and_b32_e32 v152, 0xffff0000, v186
	v_pk_mul_f32 v[152:153], v[154:155], v[152:153]
	s_waitcnt vmcnt(1)
	v_and_b32_e32 v154, 0xffff0000, v179
	v_pk_mul_f32 v[152:153], v[16:17], v[152:153]
	v_mul_f32_e32 v154, v157, v154
	v_add_f32_e32 v186, v159, v153
	v_add_f32_e32 v186, v152, v186
	v_lshlrev_b32_e32 v152, 16, v178
	v_and_b32_e32 v153, 0xffff0000, v178
	v_mul_f32_e32 v152, v172, v152
	v_mul_f32_e32 v153, v156, v153
	v_cvt_pk_bf16_f32 v152, v152, v153
	v_lshlrev_b32_e32 v153, 16, v179
	v_mul_f32_e32 v153, v162, v153
	v_cvt_pk_bf16_f32 v153, v153, v154
	v_lshlrev_b32_e32 v154, 16, v180
	v_and_b32_e32 v155, 0xffff0000, v180
	v_mul_f32_e32 v154, v163, v154
	v_mul_f32_e32 v155, v158, v155
	v_cvt_pk_bf16_f32 v154, v154, v155
	v_lshlrev_b32_e32 v155, 16, v181
	v_and_b32_e32 v156, 0xffff0000, v181
	v_mul_f32_e32 v155, v164, v155
	v_mul_f32_e32 v186, v186, v156
	v_lshl_add_u64 v[156:157], v[30:31], 0, v[64:65]
	v_lshl_add_u64 v[30:31], v[30:31], 0, s[62:63]
	v_cvt_pk_bf16_f32 v155, v155, v186
	global_store_dwordx4 v[156:157], v[152:155], off
	s_cbranch_scc0 .LBB0_390
; __device__ __forceinline__ float bflo(unsigned w) { return __uint_as_float(w << 16); }
; __device__ __forceinline__ float bfhi(unsigned w) { return __uint_as_float(w & 0xffff0000u); }
; __device__ __forceinline__ float sigmoid_f(float x) { return __builtin_amdgcn_rcpf(1.0f + __builtin_amdgcn_exp2f(-1.4426950408889634f * x)); }
; #define LAS __attribute__((address_space(3)))
; __device__ __forceinline__ void conv_unit(LAS unsigned char* lds, const bf16_t* PROJ, bf16_t* YCAT, const float* wshort, const float* dwb, const float* lng, const float* lnb, int bg, int bl, int tb, int tid, int wave, int lane) {
;     ...
;     {
;         u32x4 ga[6], gs[6];
; #pragma unroll
;         for (int it = 0; it < 6; ++it) {
;             const int idx = tid + 512 * it, idc = idx < 94 * 32 ? idx : 94 * 32 - 1, r = idc >> 5, grp = idc & 31, tt = t0 - 30 + r, ttc = tt < 0 ? 0 : tt;
;             const bf16_t* src = PROJ + (prow + ttc) * NPROJ + 1536 + 8 * grp;
;             ga[it] = *(const u32x4*)src; gs[it] = *(const u32x4*)(src + 256);
;         }
; #pragma unroll
;         for (int it = 0; it < 6; ++it) {
;             const int idx = tid + 512 * it, r = idx >> 5, grp = idx & 31, tt = t0 - 30 + r;
;             u32x4 a = ga[it]; const u32x4 sg = gs[it];
;             if (tt < 0) a = (u32x4){0u, 0u, 0u, 0u};
;             f32x4 g0, g1;
;             g0[0] = bflo(a.x) * sigmoid_f(bflo(sg.x)); g0[1] = bfhi(a.x) * sigmoid_f(bfhi(sg.x)); g0[2] = bflo(a.y) * sigmoid_f(bflo(sg.y)); g0[3] = bfhi(a.y) * sigmoid_f(bfhi(sg.y));
;             g1[0] = bflo(a.z) * sigmoid_f(bflo(sg.z)); g1[1] = bfhi(a.z) * sigmoid_f(bfhi(sg.z)); g1[2] = bflo(a.w) * sigmoid_f(bflo(sg.w)); g1[3] = bfhi(a.w) * sigmoid_f(bfhi(sg.w));
;             if (idx < 94 * 32) { *(LAS f32x4*)(glu + r * 256 + 8 * grp) = g0; *(LAS f32x4*)(glu + r * 256 + 8 * grp + 4) = g1; }
;         }
	s_lshl_b32 s1, s49, 6
	s_and_b32 s3, s1, 0x7c0
	s_sub_i32 s1, s3, 30
	v_add_u32_e32 v0, s1, v120
	v_max_i32_e32 v0, 0, v0
	v_lshl_add_u64 v[2:3], s[36:37], 0, v[0:1]
	v_add_u32_e32 v0, s1, v121
	v_mad_u64_u32 v[4:5], s[18:19], v2, s50, v[52:53]
	v_max_i32_e32 v0, 0, v0
	v_mad_i32_i24 v5, v3, s50, v5
	v_lshl_add_u64 v[2:3], s[36:37], 0, v[0:1]
	v_add_u32_e32 v0, s1, v122
	global_load_dwordx4 v[38:41], v[4:5], off offset:3072
	global_load_dwordx4 v[34:37], v[4:5], off offset:3584
	v_mad_u64_u32 v[4:5], s[18:19], v2, s50, v[54:55]
	v_max_i32_e32 v0, 0, v0
	v_mad_i32_i24 v5, v3, s50, v5
	v_lshl_add_u64 v[2:3], s[36:37], 0, v[0:1]
	v_add_u32_e32 v0, s1, v123
	global_load_dwordx4 v[30:33], v[4:5], off offset:3072
	global_load_dwordx4 v[26:29], v[4:5], off offset:3584
	v_mad_u64_u32 v[4:5], s[18:19], v2, s50, v[56:57]
	v_max_i32_e32 v0, 0, v0
	v_mad_i32_i24 v5, v3, s50, v5
	v_lshl_add_u64 v[2:3], s[36:37], 0, v[0:1]
	v_add_u32_e32 v0, s1, v124
	global_load_dwordx4 v[22:25], v[4:5], off offset:3072
	global_load_dwordx4 v[18:21], v[4:5], off offset:3584
	v_mad_u64_u32 v[4:5], s[18:19], v2, s50, v[58:59]
	v_max_i32_e32 v0, 0, v0
	v_mad_i32_i24 v5, v3, s50, v5
	v_lshl_add_u64 v[2:3], s[36:37], 0, v[0:1]
	global_load_dwordx4 v[14:17], v[4:5], off offset:3072
	global_load_dwordx4 v[10:13], v[4:5], off offset:3584
	v_mad_u64_u32 v[4:5], s[18:19], v2, s50, v[60:61]
	v_mad_i32_i24 v5, v3, s50, v5
	global_load_dwordx4 v[6:9], v[4:5], off offset:3072
	s_nop 0
	global_load_dwordx4 v[2:5], v[4:5], off offset:3584
	s_sub_i32 s4, 30, s3
	s_and_saveexec_b64 s[20:21], s[14:15]
	s_cbranch_execz .LBB0_397
	v_add_u32_e32 v0, s1, v44
	v_max_i32_e32 v0, 0, v0
	v_lshl_add_u64 v[68:69], s[36:37], 0, v[0:1]
	v_mad_u64_u32 v[72:73], s[18:19], v68, s50, v[62:63]
	v_mad_i32_i24 v73, v69, s50, v73
	global_load_dwordx4 v[68:71], v[72:73], off offset:3584
	s_nop 0
	global_load_dwordx4 v[72:75], v[72:73], off offset:3072
	v_cmp_le_i32_e32 vcc, s4, v44
	s_waitcnt vmcnt(1)
	v_and_b32_e32 v0, 0xffff0000, v71
	v_lshlrev_b32_e32 v71, 16, v71
	v_mul_f32_e32 v71, 0xbfb8aa3b, v71
	s_waitcnt vmcnt(0)
	v_cndmask_b32_e32 v67, 0, v72, vcc
	v_exp_f32_e32 v71, v71
	v_and_b32_e32 v72, 0xffff0000, v69
	v_lshlrev_b32_e32 v69, 16, v69
	v_mul_f32_e32 v69, 0xbfb8aa3b, v69
	v_exp_f32_e32 v69, v69
	v_add_f32_e32 v71, 1.0, v71
	v_rcp_f32_e32 v76, v71
	v_and_b32_e32 v71, 0xffff0000, v70
	v_lshlrev_b32_e32 v70, 16, v70
	v_mul_f32_e32 v71, 0xbfb8aa3b, v71
	v_mul_f32_e32 v70, 0xbfb8aa3b, v70
	v_add_f32_e32 v69, 1.0, v69
	v_mul_f32_e32 v0, 0xbfb8aa3b, v0
	v_cndmask_b32_e32 v79, 0, v74, vcc
	v_exp_f32_e32 v71, v71
	v_exp_f32_e32 v70, v70
	v_rcp_f32_e32 v74, v69
	v_and_b32_e32 v69, 0xffff0000, v68
	v_lshlrev_b32_e32 v68, 16, v68
	v_exp_f32_e32 v0, v0
	v_mul_f32_e32 v72, 0xbfb8aa3b, v72
	v_mul_f32_e32 v69, 0xbfb8aa3b, v69
	v_mul_f32_e32 v68, 0xbfb8aa3b, v68
	v_exp_f32_e32 v72, v72
	v_exp_f32_e32 v69, v69
	v_exp_f32_e32 v68, v68
	v_add_f32_e32 v71, 1.0, v71
	v_add_f32_e32 v70, 1.0, v70
	v_add_f32_e32 v0, 1.0, v0
	v_rcp_f32_e32 v71, v71
	v_rcp_f32_e32 v70, v70
	v_rcp_f32_e32 v77, v0
	v_add_f32_e32 v72, 1.0, v72
	v_add_f32_e32 v69, 1.0, v69
	v_add_f32_e32 v68, 1.0, v68
	v_cndmask_b32_e32 v0, 0, v73, vcc
	v_cndmask_b32_e32 v78, 0, v75, vcc
	v_rcp_f32_e32 v75, v72
	v_rcp_f32_e32 v73, v69
	v_rcp_f32_e32 v72, v68
	v_lshlrev_b32_e32 v68, 16, v79
	v_and_b32_e32 v69, 0xffff0000, v79
	v_pk_mul_f32 v[68:69], v[70:71], v[68:69]
	v_lshlrev_b32_e32 v70, 16, v78
	v_and_b32_e32 v71, 0xffff0000, v78
	v_pk_mul_f32 v[70:71], v[76:77], v[70:71]
	v_lshlrev_b32_e32 v76, 16, v67
	v_and_b32_e32 v77, 0xffff0000, v67
	v_pk_mul_f32 v[72:73], v[72:73], v[76:77]
	v_lshlrev_b32_e32 v76, 16, v0
	v_and_b32_e32 v77, 0xffff0000, v0
	v_pk_mul_f32 v[74:75], v[74:75], v[76:77]
	ds_write_b128 v133, v[72:75]
	ds_write_b128 v133, v[68:71] offset:16
	s_or_b64 exec, exec, s[20:21]
	s_and_saveexec_b64 s[20:21], s[16:17]
	s_cbranch_execnz .LBB0_398
